# P8 epilogue: 32 residual loads hoisted, counted vmcnt(31)
# baseline (speedup 1.0000x reference)
.LBB0_1058:
	v_lshl_add_u32 v144, s35, 8, v133
	s_lshl_b32 s14, s36, 8
	v_or_b32_e32 v142, s14, v132
	v_lshl_add_u32 v142, v144, 10, v142
	v_lshlrev_b32_e32 v143, 2, v142
	v_lshlrev_b32_e32 v142, 1, v142
	s_and_b64 vcc, exec, s[0:1]
	s_mov_b64 s[0:1], -1
	global_load_dwordx2 v[150:151], v142, s[82:83]
	global_load_dwordx2 v[152:153], v142, s[82:83] offset:32
	global_load_dwordx2 v[154:155], v142, s[82:83] offset:256
	global_load_dwordx2 v[156:157], v142, s[82:83] offset:288
	v_add_u32_e32 v144, 0x8000, v142
	global_load_dwordx2 v[158:159], v144, s[82:83]
	global_load_dwordx2 v[160:161], v144, s[82:83] offset:32
	global_load_dwordx2 v[162:163], v144, s[82:83] offset:256
	global_load_dwordx2 v[164:165], v144, s[82:83] offset:288
	v_add_u32_e32 v144, 0x10000, v142
	global_load_dwordx2 v[166:167], v144, s[82:83]
	global_load_dwordx2 v[168:169], v144, s[82:83] offset:32
	global_load_dwordx2 v[170:171], v144, s[82:83] offset:256
	global_load_dwordx2 v[172:173], v144, s[82:83] offset:288
	v_add_u32_e32 v144, 0x18000, v142
	global_load_dwordx2 v[174:175], v144, s[82:83]
	global_load_dwordx2 v[176:177], v144, s[82:83] offset:32
	global_load_dwordx2 v[178:179], v144, s[82:83] offset:256
	global_load_dwordx2 v[180:181], v144, s[82:83] offset:288
	v_add_u32_e32 v144, 0x40000, v142
	global_load_dwordx2 v[182:183], v144, s[82:83]
	global_load_dwordx2 v[184:185], v144, s[82:83] offset:32
	global_load_dwordx2 v[186:187], v144, s[82:83] offset:256
	global_load_dwordx2 v[188:189], v144, s[82:83] offset:288
	v_add_u32_e32 v144, 0x48000, v142
	global_load_dwordx2 v[190:191], v144, s[82:83]
	global_load_dwordx2 v[194:195], v144, s[82:83] offset:32
	global_load_dwordx2 v[196:197], v144, s[82:83] offset:256
	global_load_dwordx2 v[198:199], v144, s[82:83] offset:288
	v_add_u32_e32 v144, 0x50000, v142
	global_load_dwordx2 v[200:201], v144, s[82:83]
	global_load_dwordx2 v[202:203], v144, s[82:83] offset:32
	global_load_dwordx2 v[204:205], v144, s[82:83] offset:256
	global_load_dwordx2 v[206:207], v144, s[82:83] offset:288
	v_add_u32_e32 v144, 0x58000, v142
	global_load_dwordx2 v[208:209], v144, s[82:83]
	global_load_dwordx2 v[210:211], v144, s[82:83] offset:32
	global_load_dwordx2 v[212:213], v144, s[82:83] offset:256
	global_load_dwordx2 v[214:215], v144, s[82:83] offset:288
	s_waitcnt vmcnt(31)
	v_lshlrev_b32_e32 v216, 16, v150
	v_and_b32_e32 v217, 0xffff0000, v150
	v_lshlrev_b32_e32 v218, 16, v151
	v_and_b32_e32 v219, 0xffff0000, v151
	v_pk_add_f32 v[124:125], v[124:125], v[216:217]
	v_pk_add_f32 v[126:127], v[126:127], v[218:219]
	global_store_dwordx4 v143, v[124:127], s[74:75] nt
	s_waitcnt vmcnt(31)
	v_lshlrev_b32_e32 v220, 16, v152
	v_and_b32_e32 v221, 0xffff0000, v152
	v_lshlrev_b32_e32 v222, 16, v153
	v_and_b32_e32 v223, 0xffff0000, v153
	v_pk_add_f32 v[120:121], v[120:121], v[220:221]
	v_pk_add_f32 v[122:123], v[122:123], v[222:223]
	global_store_dwordx4 v143, v[120:123], s[74:75] offset:64 nt
	s_waitcnt vmcnt(31)
	v_lshlrev_b32_e32 v216, 16, v154
	v_and_b32_e32 v217, 0xffff0000, v154
	v_lshlrev_b32_e32 v218, 16, v155
	v_and_b32_e32 v219, 0xffff0000, v155
	v_pk_add_f32 v[116:117], v[116:117], v[216:217]
	v_pk_add_f32 v[118:119], v[118:119], v[218:219]
	global_store_dwordx4 v143, v[116:119], s[74:75] offset:512 nt
	s_waitcnt vmcnt(31)
	v_lshlrev_b32_e32 v220, 16, v156
	v_and_b32_e32 v221, 0xffff0000, v156
	v_lshlrev_b32_e32 v222, 16, v157
	v_and_b32_e32 v223, 0xffff0000, v157
	v_pk_add_f32 v[112:113], v[112:113], v[220:221]
	v_pk_add_f32 v[114:115], v[114:115], v[222:223]
	global_store_dwordx4 v143, v[112:115], s[74:75] offset:576 nt
	v_add_u32_e32 v145, 0x10000, v143
	s_waitcnt vmcnt(31)
	v_lshlrev_b32_e32 v216, 16, v158
	v_and_b32_e32 v217, 0xffff0000, v158
	v_lshlrev_b32_e32 v218, 16, v159
	v_and_b32_e32 v219, 0xffff0000, v159
	v_pk_add_f32 v[108:109], v[108:109], v[216:217]
	v_pk_add_f32 v[110:111], v[110:111], v[218:219]
	global_store_dwordx4 v145, v[108:111], s[74:75] nt
	s_waitcnt vmcnt(31)
	v_lshlrev_b32_e32 v220, 16, v160
	v_and_b32_e32 v221, 0xffff0000, v160
	v_lshlrev_b32_e32 v222, 16, v161
	v_and_b32_e32 v223, 0xffff0000, v161
	v_pk_add_f32 v[104:105], v[104:105], v[220:221]
	v_pk_add_f32 v[106:107], v[106:107], v[222:223]
	global_store_dwordx4 v145, v[104:107], s[74:75] offset:64 nt
	s_waitcnt vmcnt(31)
	v_lshlrev_b32_e32 v216, 16, v162
	v_and_b32_e32 v217, 0xffff0000, v162
	v_lshlrev_b32_e32 v218, 16, v163
	v_and_b32_e32 v219, 0xffff0000, v163
	v_pk_add_f32 v[100:101], v[100:101], v[216:217]
	v_pk_add_f32 v[102:103], v[102:103], v[218:219]
	global_store_dwordx4 v145, v[100:103], s[74:75] offset:512 nt
	s_waitcnt vmcnt(31)
	v_lshlrev_b32_e32 v220, 16, v164
	v_and_b32_e32 v221, 0xffff0000, v164
	v_lshlrev_b32_e32 v222, 16, v165
	v_and_b32_e32 v223, 0xffff0000, v165
	v_pk_add_f32 v[96:97], v[96:97], v[220:221]
	v_pk_add_f32 v[98:99], v[98:99], v[222:223]
	global_store_dwordx4 v145, v[96:99], s[74:75] offset:576 nt
	v_add_u32_e32 v145, 0x20000, v143
	s_waitcnt vmcnt(31)
	v_lshlrev_b32_e32 v216, 16, v166
	v_and_b32_e32 v217, 0xffff0000, v166
	v_lshlrev_b32_e32 v218, 16, v167
	v_and_b32_e32 v219, 0xffff0000, v167
	v_pk_add_f32 v[92:93], v[92:93], v[216:217]
	v_pk_add_f32 v[94:95], v[94:95], v[218:219]
	global_store_dwordx4 v145, v[92:95], s[74:75] nt
	s_waitcnt vmcnt(31)
	v_lshlrev_b32_e32 v220, 16, v168
	v_and_b32_e32 v221, 0xffff0000, v168
	v_lshlrev_b32_e32 v222, 16, v169
	v_and_b32_e32 v223, 0xffff0000, v169
	v_pk_add_f32 v[88:89], v[88:89], v[220:221]
	v_pk_add_f32 v[90:91], v[90:91], v[222:223]
	global_store_dwordx4 v145, v[88:91], s[74:75] offset:64 nt
	s_waitcnt vmcnt(31)
	v_lshlrev_b32_e32 v216, 16, v170
	v_and_b32_e32 v217, 0xffff0000, v170
	v_lshlrev_b32_e32 v218, 16, v171
	v_and_b32_e32 v219, 0xffff0000, v171
	v_pk_add_f32 v[84:85], v[84:85], v[216:217]
	v_pk_add_f32 v[86:87], v[86:87], v[218:219]
	global_store_dwordx4 v145, v[84:87], s[74:75] offset:512 nt
	s_waitcnt vmcnt(31)
	v_lshlrev_b32_e32 v220, 16, v172
	v_and_b32_e32 v221, 0xffff0000, v172
	v_lshlrev_b32_e32 v222, 16, v173
	v_and_b32_e32 v223, 0xffff0000, v173
	v_pk_add_f32 v[80:81], v[80:81], v[220:221]
	v_pk_add_f32 v[82:83], v[82:83], v[222:223]
	global_store_dwordx4 v145, v[80:83], s[74:75] offset:576 nt
	v_add_u32_e32 v145, 0x30000, v143
	s_waitcnt vmcnt(31)
	v_lshlrev_b32_e32 v216, 16, v174
	v_and_b32_e32 v217, 0xffff0000, v174
	v_lshlrev_b32_e32 v218, 16, v175
	v_and_b32_e32 v219, 0xffff0000, v175
	v_pk_add_f32 v[76:77], v[76:77], v[216:217]
	v_pk_add_f32 v[78:79], v[78:79], v[218:219]
	global_store_dwordx4 v145, v[76:79], s[74:75] nt
	s_waitcnt vmcnt(31)
	v_lshlrev_b32_e32 v220, 16, v176
	v_and_b32_e32 v221, 0xffff0000, v176
	v_lshlrev_b32_e32 v222, 16, v177
	v_and_b32_e32 v223, 0xffff0000, v177
	v_pk_add_f32 v[72:73], v[72:73], v[220:221]
	v_pk_add_f32 v[74:75], v[74:75], v[222:223]
	global_store_dwordx4 v145, v[72:75], s[74:75] offset:64 nt
	s_waitcnt vmcnt(31)
	v_lshlrev_b32_e32 v216, 16, v178
	v_and_b32_e32 v217, 0xffff0000, v178
	v_lshlrev_b32_e32 v218, 16, v179
	v_and_b32_e32 v219, 0xffff0000, v179
	v_pk_add_f32 v[68:69], v[68:69], v[216:217]
	v_pk_add_f32 v[70:71], v[70:71], v[218:219]
	global_store_dwordx4 v145, v[68:71], s[74:75] offset:512 nt
	s_waitcnt vmcnt(31)
	v_lshlrev_b32_e32 v220, 16, v180
	v_and_b32_e32 v221, 0xffff0000, v180
	v_lshlrev_b32_e32 v222, 16, v181
	v_and_b32_e32 v223, 0xffff0000, v181
	v_pk_add_f32 v[64:65], v[64:65], v[220:221]
	v_pk_add_f32 v[66:67], v[66:67], v[222:223]
	global_store_dwordx4 v145, v[64:67], s[74:75] offset:576 nt
	v_add_u32_e32 v145, 0x80000, v143
	s_waitcnt vmcnt(31)
	v_lshlrev_b32_e32 v216, 16, v182
	v_and_b32_e32 v217, 0xffff0000, v182
	v_lshlrev_b32_e32 v218, 16, v183
	v_and_b32_e32 v219, 0xffff0000, v183
	v_pk_add_f32 v[60:61], v[60:61], v[216:217]
	v_pk_add_f32 v[62:63], v[62:63], v[218:219]
	global_store_dwordx4 v145, v[60:63], s[74:75] nt
	s_waitcnt vmcnt(31)
	v_lshlrev_b32_e32 v220, 16, v184
	v_and_b32_e32 v221, 0xffff0000, v184
	v_lshlrev_b32_e32 v222, 16, v185
	v_and_b32_e32 v223, 0xffff0000, v185
	v_pk_add_f32 v[56:57], v[56:57], v[220:221]
	v_pk_add_f32 v[58:59], v[58:59], v[222:223]
	global_store_dwordx4 v145, v[56:59], s[74:75] offset:64 nt
	s_waitcnt vmcnt(31)
	v_lshlrev_b32_e32 v216, 16, v186
	v_and_b32_e32 v217, 0xffff0000, v186
	v_lshlrev_b32_e32 v218, 16, v187
	v_and_b32_e32 v219, 0xffff0000, v187
	v_pk_add_f32 v[52:53], v[52:53], v[216:217]
	v_pk_add_f32 v[54:55], v[54:55], v[218:219]
	global_store_dwordx4 v145, v[52:55], s[74:75] offset:512 nt
	s_waitcnt vmcnt(31)
	v_lshlrev_b32_e32 v220, 16, v188
	v_and_b32_e32 v221, 0xffff0000, v188
	v_lshlrev_b32_e32 v222, 16, v189
	v_and_b32_e32 v223, 0xffff0000, v189
	v_pk_add_f32 v[48:49], v[48:49], v[220:221]
	v_pk_add_f32 v[50:51], v[50:51], v[222:223]
	global_store_dwordx4 v145, v[48:51], s[74:75] offset:576 nt
	v_add_u32_e32 v145, 0x90000, v143
	s_waitcnt vmcnt(31)
	v_lshlrev_b32_e32 v216, 16, v190
	v_and_b32_e32 v217, 0xffff0000, v190
	v_lshlrev_b32_e32 v218, 16, v191
	v_and_b32_e32 v219, 0xffff0000, v191
	v_pk_add_f32 v[44:45], v[44:45], v[216:217]
	v_pk_add_f32 v[46:47], v[46:47], v[218:219]
	global_store_dwordx4 v145, v[44:47], s[74:75] nt
	s_waitcnt vmcnt(31)
	v_lshlrev_b32_e32 v220, 16, v194
	v_and_b32_e32 v221, 0xffff0000, v194
	v_lshlrev_b32_e32 v222, 16, v195
	v_and_b32_e32 v223, 0xffff0000, v195
	v_pk_add_f32 v[40:41], v[40:41], v[220:221]
	v_pk_add_f32 v[42:43], v[42:43], v[222:223]
	global_store_dwordx4 v145, v[40:43], s[74:75] offset:64 nt
	s_waitcnt vmcnt(31)
	v_lshlrev_b32_e32 v216, 16, v196
	v_and_b32_e32 v217, 0xffff0000, v196
	v_lshlrev_b32_e32 v218, 16, v197
	v_and_b32_e32 v219, 0xffff0000, v197
	v_pk_add_f32 v[36:37], v[36:37], v[216:217]
	v_pk_add_f32 v[38:39], v[38:39], v[218:219]
	global_store_dwordx4 v145, v[36:39], s[74:75] offset:512 nt
	s_waitcnt vmcnt(31)
	v_lshlrev_b32_e32 v220, 16, v198
	v_and_b32_e32 v221, 0xffff0000, v198
	v_lshlrev_b32_e32 v222, 16, v199
	v_and_b32_e32 v223, 0xffff0000, v199
	v_pk_add_f32 v[32:33], v[32:33], v[220:221]
	v_pk_add_f32 v[34:35], v[34:35], v[222:223]
	global_store_dwordx4 v145, v[32:35], s[74:75] offset:576 nt
	v_add_u32_e32 v145, 0xa0000, v143
	s_waitcnt vmcnt(31)
	v_lshlrev_b32_e32 v216, 16, v200
	v_and_b32_e32 v217, 0xffff0000, v200
	v_lshlrev_b32_e32 v218, 16, v201
	v_and_b32_e32 v219, 0xffff0000, v201
	v_pk_add_f32 v[28:29], v[28:29], v[216:217]
	v_pk_add_f32 v[30:31], v[30:31], v[218:219]
	global_store_dwordx4 v145, v[28:31], s[74:75] nt
	s_waitcnt vmcnt(31)
	v_lshlrev_b32_e32 v220, 16, v202
	v_and_b32_e32 v221, 0xffff0000, v202
	v_lshlrev_b32_e32 v222, 16, v203
	v_and_b32_e32 v223, 0xffff0000, v203
	v_pk_add_f32 v[24:25], v[24:25], v[220:221]
	v_pk_add_f32 v[26:27], v[26:27], v[222:223]
	global_store_dwordx4 v145, v[24:27], s[74:75] offset:64 nt
	s_waitcnt vmcnt(31)
	v_lshlrev_b32_e32 v216, 16, v204
	v_and_b32_e32 v217, 0xffff0000, v204
	v_lshlrev_b32_e32 v218, 16, v205
	v_and_b32_e32 v219, 0xffff0000, v205
	v_pk_add_f32 v[20:21], v[20:21], v[216:217]
	v_pk_add_f32 v[22:23], v[22:23], v[218:219]
	global_store_dwordx4 v145, v[20:23], s[74:75] offset:512 nt
	s_waitcnt vmcnt(31)
	v_lshlrev_b32_e32 v220, 16, v206
	v_and_b32_e32 v221, 0xffff0000, v206
	v_lshlrev_b32_e32 v222, 16, v207
	v_and_b32_e32 v223, 0xffff0000, v207
	v_pk_add_f32 v[16:17], v[16:17], v[220:221]
	v_pk_add_f32 v[18:19], v[18:19], v[222:223]
	global_store_dwordx4 v145, v[16:19], s[74:75] offset:576 nt
	v_add_u32_e32 v145, 0xb0000, v143
	s_waitcnt vmcnt(31)
	v_lshlrev_b32_e32 v216, 16, v208
	v_and_b32_e32 v217, 0xffff0000, v208
	v_lshlrev_b32_e32 v218, 16, v209
	v_and_b32_e32 v219, 0xffff0000, v209
	v_pk_add_f32 v[12:13], v[12:13], v[216:217]
	v_pk_add_f32 v[14:15], v[14:15], v[218:219]
	global_store_dwordx4 v145, v[12:15], s[74:75] nt
	s_waitcnt vmcnt(31)
	v_lshlrev_b32_e32 v220, 16, v210
	v_and_b32_e32 v221, 0xffff0000, v210
	v_lshlrev_b32_e32 v222, 16, v211
	v_and_b32_e32 v223, 0xffff0000, v211
	v_pk_add_f32 v[8:9], v[8:9], v[220:221]
	v_pk_add_f32 v[10:11], v[10:11], v[222:223]
	global_store_dwordx4 v145, v[8:11], s[74:75] offset:64 nt
	s_waitcnt vmcnt(31)
	v_lshlrev_b32_e32 v216, 16, v212
	v_and_b32_e32 v217, 0xffff0000, v212
	v_lshlrev_b32_e32 v218, 16, v213
	v_and_b32_e32 v219, 0xffff0000, v213
	v_pk_add_f32 v[4:5], v[4:5], v[216:217]
	v_pk_add_f32 v[6:7], v[6:7], v[218:219]
	global_store_dwordx4 v145, v[4:7], s[74:75] offset:512 nt
	s_waitcnt vmcnt(31)
	v_lshlrev_b32_e32 v220, 16, v214
	v_and_b32_e32 v221, 0xffff0000, v214
	v_lshlrev_b32_e32 v222, 16, v215
	v_and_b32_e32 v223, 0xffff0000, v215
	v_pk_add_f32 v[0:1], v[0:1], v[220:221]
	v_pk_add_f32 v[2:3], v[2:3], v[222:223]
	global_store_dwordx4 v145, v[0:3], s[74:75] offset:576 nt
	s_cbranch_vccnz .LBB0_1043
	s_andn2_b64 vcc, exec, s[6:7]
	s_cbranch_vccnz .LBB0_1042
	s_barrier
	s_branch .LBB0_1042
